# first two K-loop DMA waits after the G1 epilogue relaxed too (on top of the G4 relax)
# baseline (speedup 1.0000x reference)
; #define PG8_STAGE(bufoff, gbase, voff) do { _Pragma("unroll") for (int _i = 0; _i < 2; ++_i) \
;         __builtin_amdgcn_global_load_lds((const unsigned*)((const char*)(gbase) + (voff)[_i]), (PG8_LAS unsigned*)(lds + (bufoff) + ldsw + _i * 8192), 16, 0, 0); } while (0)
; #define PG8_LDA(dst, b, h) do { _Pragma("unroll") for (int m = 0; m < 4; ++m) _Pragma("unroll") for (int k = 0; k < 2; ++k) dst[m][k] = *(const PG8_LAS bf16x8*)(lds + PG8_SA(b, h) + aoff + m * 2048 + k * 1024); } while (0)
; #define PG8_LDB(dst, b, h) do { _Pragma("unroll") for (int n = 0; n < 2; ++n) _Pragma("unroll") for (int k = 0; k < 2; ++k) dst[n][k] = *(const PG8_LAS bf16x8*)(lds + PG8_SB(b, h) + boff + n * 2048 + k * 1024); } while (0)
; #define PG8_WAIT_V(n) asm volatile("s_waitcnt vmcnt(" #n ")" ::: "memory")
; #define PG8_WAIT_L(n) asm volatile("s_waitcnt lgkmcnt(" #n ")" ::: "memory")
; #define PG8_BAR __builtin_amdgcn_s_barrier()
; #define PG8_SCHED __builtin_amdgcn_sched_barrier(0)
; template <class Epi, class Sched, bool ALIGN_EPI = false, bool SP2 = false>
; __device__ __forceinline__ void gemm_phase(PG8_LAS unsigned char* lds, const Gemm g, const Sched& S, const Epi& E) {
;     ...
;         const bool has_next = S.next(ui + 1, nxt);
;         const char* nA = has_next ? (const char*)g.A + (size_t)nxt.pm * tstep : cA; const char* nB = has_next ? (const char*)g.Bt + (size_t)nxt.pn * tstep : cB;
;         for (int t = 0; t < nt; t += 2) {
;             const bool last = (t == nt - 2);
;             const char* a1 = cA + (size_t)(t + 1) * kstep;
;             const char* a2 = last ? nA : cA + (size_t)(t + 2) * kstep; const char* b2 = last ? nB : cB + (size_t)(t + 2) * kstep;
;             const char* a3 = a2 + kstep; const char* b3 = b2 + kstep;
;             if (last && has_next) S.a_ready(nxt);
;             if constexpr (SP2) {
;             PG8_LDB(B0, 0, 0); PG8_LDB(B1, 0, 1); PG8_SCHED; PG8_LDA(At, 0, 0); PG8_STAGE(PG8_SA(1, 1), a1 + hstep, voffA);
;             PG8_WAIT_V(8); PG8_WAIT_L(0); PG8_BAR; PG8_MMA(0, 0, At, B0); PG8_MMA(0, 1, At, B1); PG8_BAR; PG8_SCHED;
;             PG8_LDA(At, 0, 1); PG8_STAGE(PG8_SB(0, 0), b2, voffB); PG8_STAGE(PG8_SB(0, 1), b2 + hstep, voffB); PG8_STAGE(PG8_SA(0, 0), a2, voffA);
;             PG8_WAIT_V(8); PG8_WAIT_L(0); PG8_BAR; PG8_MMA(1, 0, At, B0); PG8_MMA(1, 1, At, B1); PG8_BAR; PG8_SCHED;
.LBB0_174:
	s_ashr_i32 s39, s38, 31
	s_lshl_b64 s[0:1], s[38:39], 19
	s_add_u32 s48, s23, s0
	s_addc_u32 s49, s12, s1
	s_and_b64 s[0:1], s[42:43], exec
	s_cselect_b32 s0, s49, s57
	s_cselect_b32 s1, s48, s56
	s_ashr_i32 s37, s36, 31
	s_lshl_b64 s[24:25], s[36:37], 19
	s_add_u32 s52, s85, s24
	s_addc_u32 s53, s86, s25
	s_and_b64 s[24:25], s[42:43], exec
	s_cselect_b32 s10, s53, s59
	s_cselect_b32 s22, s52, s58
	s_add_u32 s56, s56, 0x40080
	s_addc_u32 s57, s57, 0
	s_add_u32 s33, s58, 0x100
	s_addc_u32 s37, s59, 0
	s_mov_b32 s39, -2
	s_waitcnt lgkmcnt(0)
	s_add_u32 s24, s56, 0xfffc0080
	s_addc_u32 s25, s57, -1
	s_add_i32 s45, 0, 0x10000
	s_cmp_eq_u32 s39, 12
	s_cselect_b32 s61, s0, s25
	s_cselect_b32 s60, s1, s24
	v_add_u32_e32 v132, s45, v192
	s_cselect_b32 s59, s10, s37
	s_cselect_b32 s58, s22, s33
	s_add_i32 s47, 0, 0x14000
	ds_read_b128 v[128:131], v132
	ds_read_b128 v[158:161], v132 offset:1024
	ds_read_b128 v[162:165], v132 offset:2048
	ds_read_b128 v[166:169], v132 offset:3072
	v_add_u32_e32 v132, s47, v192
	ds_read_b128 v[194:197], v132
	ds_read_b128 v[198:201], v132 offset:1024
	ds_read_b128 v[202:205], v132 offset:2048
	ds_read_b128 v[206:209], v132 offset:3072
	v_lshl_add_u64 v[170:171], s[56:57], 0, v[154:155]
	s_add_i32 m0, s73, 0xc000
	ds_read_b128 v[210:213], v193
	ds_read_b128 v[214:217], v193 offset:1024
	ds_read_b128 v[218:221], v193 offset:2048
	ds_read_b128 v[222:225], v193 offset:3072
	ds_read_b128 v[226:229], v193 offset:4096
	ds_read_b128 v[230:233], v193 offset:5120
	ds_read_b128 v[234:237], v193 offset:6144
	ds_read_b128 v[238:241], v193 offset:7168
	global_load_lds_dwordx4 v[170:171], off
	v_lshl_add_u64 v[170:171], s[56:57], 0, v[156:157]
	s_add_i32 m0, s73, 0xe000
	s_nop 0
	global_load_lds_dwordx4 v[170:171], off
	s_waitcnt vmcnt(32)
	s_waitcnt lgkmcnt(0)
	s_barrier
	s_setprio 1
	v_mfma_f32_16x16x32_bf16 v[124:127], v[128:131], v[210:213], 0
	v_mfma_f32_16x16x32_bf16 v[120:123], v[162:165], v[210:213], 0
	v_mfma_f32_16x16x32_bf16 v[108:111], v[128:131], v[218:221], 0
	v_mfma_f32_16x16x32_bf16 v[104:107], v[162:165], v[218:221], 0
	v_mfma_f32_16x16x32_bf16 v[92:95], v[128:131], v[226:229], 0
	v_mfma_f32_16x16x32_bf16 v[88:91], v[162:165], v[226:229], 0
	v_mfma_f32_16x16x32_bf16 v[76:79], v[128:131], v[234:237], 0
	v_mfma_f32_16x16x32_bf16 v[72:75], v[162:165], v[234:237], 0
	v_mfma_f32_16x16x32_bf16 v[124:127], v[158:161], v[214:217], v[124:127]
	v_mfma_f32_16x16x32_bf16 v[120:123], v[166:169], v[214:217], v[120:123]
	v_mfma_f32_16x16x32_bf16 v[108:111], v[158:161], v[222:225], v[108:111]
	v_mfma_f32_16x16x32_bf16 v[104:107], v[166:169], v[222:225], v[104:107]
	v_mfma_f32_16x16x32_bf16 v[92:95], v[158:161], v[230:233], v[92:95]
	v_mfma_f32_16x16x32_bf16 v[88:91], v[166:169], v[230:233], v[88:91]
	v_mfma_f32_16x16x32_bf16 v[76:79], v[158:161], v[238:241], v[76:79]
	v_mfma_f32_16x16x32_bf16 v[72:75], v[166:169], v[238:241], v[72:75]
	v_mfma_f32_16x16x32_bf16 v[116:119], v[194:197], v[210:213], 0
	v_mfma_f32_16x16x32_bf16 v[112:115], v[202:205], v[210:213], 0
	v_mfma_f32_16x16x32_bf16 v[100:103], v[194:197], v[218:221], 0
	v_mfma_f32_16x16x32_bf16 v[96:99], v[202:205], v[218:221], 0
	v_mfma_f32_16x16x32_bf16 v[84:87], v[194:197], v[226:229], 0
	v_mfma_f32_16x16x32_bf16 v[80:83], v[202:205], v[226:229], 0
	v_mfma_f32_16x16x32_bf16 v[68:71], v[194:197], v[234:237], 0
	v_mfma_f32_16x16x32_bf16 v[64:67], v[202:205], v[234:237], 0
	v_mfma_f32_16x16x32_bf16 v[116:119], v[198:201], v[214:217], v[116:119]
	v_mfma_f32_16x16x32_bf16 v[112:115], v[206:209], v[214:217], v[112:115]
	v_mfma_f32_16x16x32_bf16 v[100:103], v[198:201], v[222:225], v[100:103]
	v_mfma_f32_16x16x32_bf16 v[96:99], v[206:209], v[222:225], v[96:99]
	v_mfma_f32_16x16x32_bf16 v[84:87], v[198:201], v[230:233], v[84:87]
	v_mfma_f32_16x16x32_bf16 v[80:83], v[206:209], v[230:233], v[80:83]
	v_mfma_f32_16x16x32_bf16 v[68:71], v[198:201], v[238:241], v[68:71]
	v_mfma_f32_16x16x32_bf16 v[64:67], v[206:209], v[238:241], v[64:67]
	s_setprio 0
	s_barrier
	s_add_i32 s24, s45, s29
	v_lshl_add_u64 v[170:171], s[58:59], 0, v[142:143]
	s_mov_b32 m0, s24
	ds_read_b128 v[210:213], v193 offset:16384
	ds_read_b128 v[214:217], v193 offset:17408
	ds_read_b128 v[218:221], v193 offset:18432
	ds_read_b128 v[222:225], v193 offset:19456
	ds_read_b128 v[226:229], v193 offset:20480
	ds_read_b128 v[230:233], v193 offset:21504
	ds_read_b128 v[234:237], v193 offset:22528
	ds_read_b128 v[238:241], v193 offset:23552
	global_load_lds_dwordx4 v[170:171], off
	s_add_i32 m0, s24, 0x2000
	s_add_u32 s24, s58, 0x40000
	v_lshl_add_u64 v[242:243], s[58:59], 0, v[146:147]
	s_addc_u32 s25, s59, 0
	s_add_i32 s45, s47, s29
	global_load_lds_dwordx4 v[242:243], off
	v_lshl_add_u64 v[244:245], s[24:25], 0, v[142:143]
	s_mov_b32 m0, s45
	v_lshl_add_u64 v[246:247], s[60:61], 0, v[144:145]
	global_load_lds_dwordx4 v[244:245], off
	v_lshl_add_u64 v[244:245], s[24:25], 0, v[146:147]
	s_add_i32 m0, s45, 0x2000
	s_nop 0
	global_load_lds_dwordx4 v[244:245], off
	v_lshl_add_u64 v[244:245], s[60:61], 0, v[140:141]
	s_mov_b32 m0, s73
	s_nop 0
	global_load_lds_dwordx4 v[244:245], off
	s_mov_b32 m0, s87
	s_nop 0
	global_load_lds_dwordx4 v[246:247], off
	s_waitcnt vmcnt(40)
	s_waitcnt lgkmcnt(0)
	s_barrier
; #define PG8_STAGE(bufoff, gbase, voff) do { _Pragma("unroll") for (int _i = 0; _i < 2; ++_i) \
;         __builtin_amdgcn_global_load_lds((const unsigned*)((const char*)(gbase) + (voff)[_i]), (PG8_LAS unsigned*)(lds + (bufoff) + ldsw + _i * 8192), 16, 0, 0); } while (0)
; #define PG8_LDA(dst, b, h) do { _Pragma("unroll") for (int m = 0; m < 4; ++m) _Pragma("unroll") for (int k = 0; k < 2; ++k) dst[m][k] = *(const PG8_LAS bf16x8*)(lds + PG8_SA(b, h) + aoff + m * 2048 + k * 1024); } while (0)
; #define PG8_LDB(dst, b, h) do { _Pragma("unroll") for (int n = 0; n < 2; ++n) _Pragma("unroll") for (int k = 0; k < 2; ++k) dst[n][k] = *(const PG8_LAS bf16x8*)(lds + PG8_SB(b, h) + boff + n * 2048 + k * 1024); } while (0)
; #define PG8_MMA(ai, bj, At, Bt) do { __builtin_amdgcn_s_setprio(1); _Pragma("unroll") for (int m = 0; m < 4; ++m) _Pragma("unroll") for (int n = 0; n < 2; ++n) _Pragma("unroll") for (int k = 0; k < 2; ++k) \
;         acc[ai][bj][m][n] = __builtin_amdgcn_mfma_f32_16x16x32_bf16(Bt[n][k], At[m][k], acc[ai][bj][m][n], 0, 0, 0); __builtin_amdgcn_s_setprio(0); } while (0)
; #define PG8_WAIT_V(n) asm volatile("s_waitcnt vmcnt(" #n ")" ::: "memory")
; #define PG8_WAIT_L(n) asm volatile("s_waitcnt lgkmcnt(" #n ")" ::: "memory")
; #define PG8_BAR __builtin_amdgcn_s_barrier()
; #define PG8_SCHED __builtin_amdgcn_sched_barrier(0)
; template <class Epi, class Sched, bool ALIGN_EPI = false, bool SP2 = false>
; __device__ __forceinline__ void gemm_phase(PG8_LAS unsigned char* lds, const Gemm g, const Sched& S, const Epi& E) {
;     ...
;             PG8_WAIT_V(8); PG8_WAIT_L(0); PG8_BAR; PG8_MMA(1, 0, At, B0); PG8_MMA(1, 1, At, B1); PG8_BAR; PG8_SCHED;
;             PG8_LDB(B0, 1, 0); PG8_LDB(B1, 1, 1); PG8_SCHED; PG8_LDA(At, 1, 0); PG8_STAGE(PG8_SA(0, 1), a2 + hstep, voffA);
;             PG8_WAIT_V(8); PG8_WAIT_L(0); PG8_BAR; PG8_MMA(0, 0, At, B0); PG8_MMA(0, 1, At, B1); PG8_BAR; PG8_SCHED;
	s_setprio 1
	v_mfma_f32_16x16x32_bf16 v[60:63], v[128:131], v[210:213], 0
	v_mfma_f32_16x16x32_bf16 v[56:59], v[162:165], v[210:213], 0
	v_mfma_f32_16x16x32_bf16 v[44:47], v[128:131], v[218:221], 0
	v_mfma_f32_16x16x32_bf16 v[40:43], v[162:165], v[218:221], 0
	v_mfma_f32_16x16x32_bf16 v[28:31], v[128:131], v[226:229], 0
	v_mfma_f32_16x16x32_bf16 v[24:27], v[162:165], v[226:229], 0
	v_mfma_f32_16x16x32_bf16 v[12:15], v[128:131], v[234:237], 0
	v_mfma_f32_16x16x32_bf16 v[8:11], v[162:165], v[234:237], 0
	v_mfma_f32_16x16x32_bf16 v[60:63], v[158:161], v[214:217], v[60:63]
	v_mfma_f32_16x16x32_bf16 v[56:59], v[166:169], v[214:217], v[56:59]
	v_mfma_f32_16x16x32_bf16 v[44:47], v[158:161], v[222:225], v[44:47]
	v_mfma_f32_16x16x32_bf16 v[40:43], v[166:169], v[222:225], v[40:43]
	v_mfma_f32_16x16x32_bf16 v[28:31], v[158:161], v[230:233], v[28:31]
	v_mfma_f32_16x16x32_bf16 v[24:27], v[166:169], v[230:233], v[24:27]
	v_mfma_f32_16x16x32_bf16 v[12:15], v[158:161], v[238:241], v[12:15]
	v_mfma_f32_16x16x32_bf16 v[8:11], v[166:169], v[238:241], v[8:11]
	v_mfma_f32_16x16x32_bf16 v[52:55], v[194:197], v[210:213], 0
	v_mfma_f32_16x16x32_bf16 v[48:51], v[202:205], v[210:213], 0
	v_mfma_f32_16x16x32_bf16 v[36:39], v[194:197], v[218:221], 0
	v_mfma_f32_16x16x32_bf16 v[32:35], v[202:205], v[218:221], 0
	v_mfma_f32_16x16x32_bf16 v[20:23], v[194:197], v[226:229], 0
	v_mfma_f32_16x16x32_bf16 v[16:19], v[202:205], v[226:229], 0
	v_mfma_f32_16x16x32_bf16 v[4:7], v[194:197], v[234:237], 0
	v_mfma_f32_16x16x32_bf16 v[0:3], v[202:205], v[234:237], 0
	v_mfma_f32_16x16x32_bf16 v[52:55], v[198:201], v[214:217], v[52:55]
	v_mfma_f32_16x16x32_bf16 v[48:51], v[206:209], v[214:217], v[48:51]
	v_mfma_f32_16x16x32_bf16 v[36:39], v[198:201], v[222:225], v[36:39]
	v_mfma_f32_16x16x32_bf16 v[32:35], v[206:209], v[222:225], v[32:35]
	v_mfma_f32_16x16x32_bf16 v[20:23], v[198:201], v[230:233], v[20:23]
	v_mfma_f32_16x16x32_bf16 v[16:19], v[206:209], v[230:233], v[16:19]
	v_mfma_f32_16x16x32_bf16 v[4:7], v[198:201], v[238:241], v[4:7]
	v_mfma_f32_16x16x32_bf16 v[0:3], v[206:209], v[238:241], v[0:3]
	s_setprio 0
	s_barrier
	s_add_i32 s45, 0, 0x18000
	v_add_u32_e32 v132, s45, v192
	s_add_i32 s47, 0, 0x1c000
	ds_read_b128 v[128:131], v132
	ds_read_b128 v[158:161], v132 offset:1024
	ds_read_b128 v[162:165], v132 offset:2048
	ds_read_b128 v[166:169], v132 offset:3072
	v_add_u32_e32 v132, s47, v192
	ds_read_b128 v[194:197], v132
	ds_read_b128 v[198:201], v132 offset:1024
	ds_read_b128 v[202:205], v132 offset:2048
	ds_read_b128 v[206:209], v132 offset:3072
	s_add_u32 s24, s60, 0x40000
	s_addc_u32 s25, s61, 0
	s_mov_b32 m0, s88
	v_lshl_add_u64 v[248:249], s[24:25], 0, v[140:141]
	ds_read_b128 v[210:213], v193 offset:32768
	ds_read_b128 v[214:217], v193 offset:33792
	ds_read_b128 v[218:221], v193 offset:34816
	ds_read_b128 v[222:225], v193 offset:35840
	ds_read_b128 v[226:229], v193 offset:36864
	ds_read_b128 v[230:233], v193 offset:37888
	ds_read_b128 v[234:237], v193 offset:38912
	ds_read_b128 v[238:241], v193 offset:39936
	global_load_lds_dwordx4 v[248:249], off
	v_lshl_add_u64 v[248:249], s[24:25], 0, v[144:145]
	s_mov_b32 m0, s89
	s_nop 0
	global_load_lds_dwordx4 v[248:249], off
	s_waitcnt vmcnt(8)
	s_waitcnt lgkmcnt(0)
	s_barrier
	s_setprio 1
	v_mfma_f32_16x16x32_bf16 v[124:127], v[128:131], v[210:213], v[124:127]
	v_mfma_f32_16x16x32_bf16 v[120:123], v[162:165], v[210:213], v[120:123]
	v_mfma_f32_16x16x32_bf16 v[108:111], v[128:131], v[218:221], v[108:111]
	v_mfma_f32_16x16x32_bf16 v[104:107], v[162:165], v[218:221], v[104:107]
	v_mfma_f32_16x16x32_bf16 v[92:95], v[128:131], v[226:229], v[92:95]
	v_mfma_f32_16x16x32_bf16 v[88:91], v[162:165], v[226:229], v[88:91]
	v_mfma_f32_16x16x32_bf16 v[76:79], v[128:131], v[234:237], v[76:79]
	v_mfma_f32_16x16x32_bf16 v[72:75], v[162:165], v[234:237], v[72:75]
	v_mfma_f32_16x16x32_bf16 v[124:127], v[158:161], v[214:217], v[124:127]
	v_mfma_f32_16x16x32_bf16 v[120:123], v[166:169], v[214:217], v[120:123]
	v_mfma_f32_16x16x32_bf16 v[108:111], v[158:161], v[222:225], v[108:111]
	v_mfma_f32_16x16x32_bf16 v[104:107], v[166:169], v[222:225], v[104:107]
	v_mfma_f32_16x16x32_bf16 v[92:95], v[158:161], v[230:233], v[92:95]
	v_mfma_f32_16x16x32_bf16 v[88:91], v[166:169], v[230:233], v[88:91]
	v_mfma_f32_16x16x32_bf16 v[76:79], v[158:161], v[238:241], v[76:79]
	v_mfma_f32_16x16x32_bf16 v[72:75], v[166:169], v[238:241], v[72:75]
	v_mfma_f32_16x16x32_bf16 v[116:119], v[194:197], v[210:213], v[116:119]
	v_mfma_f32_16x16x32_bf16 v[112:115], v[202:205], v[210:213], v[112:115]
	v_mfma_f32_16x16x32_bf16 v[100:103], v[194:197], v[218:221], v[100:103]
	v_mfma_f32_16x16x32_bf16 v[96:99], v[202:205], v[218:221], v[96:99]
	v_mfma_f32_16x16x32_bf16 v[84:87], v[194:197], v[226:229], v[84:87]
	v_mfma_f32_16x16x32_bf16 v[80:83], v[202:205], v[226:229], v[80:83]
	v_mfma_f32_16x16x32_bf16 v[68:71], v[194:197], v[234:237], v[68:71]
	v_mfma_f32_16x16x32_bf16 v[64:67], v[202:205], v[234:237], v[64:67]
	v_mfma_f32_16x16x32_bf16 v[116:119], v[198:201], v[214:217], v[116:119]
	v_mfma_f32_16x16x32_bf16 v[112:115], v[206:209], v[214:217], v[112:115]
	v_mfma_f32_16x16x32_bf16 v[100:103], v[198:201], v[222:225], v[100:103]
	v_mfma_f32_16x16x32_bf16 v[96:99], v[206:209], v[222:225], v[96:99]
	v_mfma_f32_16x16x32_bf16 v[84:87], v[198:201], v[230:233], v[84:87]
	v_mfma_f32_16x16x32_bf16 v[80:83], v[206:209], v[230:233], v[80:83]
	v_mfma_f32_16x16x32_bf16 v[68:71], v[198:201], v[238:241], v[68:71]
	v_mfma_f32_16x16x32_bf16 v[64:67], v[206:209], v[238:241], v[64:67]
	s_setprio 0
	s_barrier
; #define PG8_STAGE(bufoff, gbase, voff) do { _Pragma("unroll") for (int _i = 0; _i < 2; ++_i) \
;         __builtin_amdgcn_global_load_lds((const unsigned*)((const char*)(gbase) + (voff)[_i]), (PG8_LAS unsigned*)(lds + (bufoff) + ldsw + _i * 8192), 16, 0, 0); } while (0)
; #define PG8_LDA(dst, b, h) do { _Pragma("unroll") for (int m = 0; m < 4; ++m) _Pragma("unroll") for (int k = 0; k < 2; ++k) dst[m][k] = *(const PG8_LAS bf16x8*)(lds + PG8_SA(b, h) + aoff + m * 2048 + k * 1024); } while (0)
; #define PG8_MMA(ai, bj, At, Bt) do { __builtin_amdgcn_s_setprio(1); _Pragma("unroll") for (int m = 0; m < 4; ++m) _Pragma("unroll") for (int n = 0; n < 2; ++n) _Pragma("unroll") for (int k = 0; k < 2; ++k) \
;         acc[ai][bj][m][n] = __builtin_amdgcn_mfma_f32_16x16x32_bf16(Bt[n][k], At[m][k], acc[ai][bj][m][n], 0, 0, 0); __builtin_amdgcn_s_setprio(0); } while (0)
; #define PG8_WAIT_V(n) asm volatile("s_waitcnt vmcnt(" #n ")" ::: "memory")
; #define PG8_WAIT_L(n) asm volatile("s_waitcnt lgkmcnt(" #n ")" ::: "memory")
; #define PG8_BAR __builtin_amdgcn_s_barrier()
; #define PG8_SCHED __builtin_amdgcn_sched_barrier(0)
; template <class Epi, class Sched, bool ALIGN_EPI = false, bool SP2 = false>
; __device__ __forceinline__ void gemm_phase(PG8_LAS unsigned char* lds, const Gemm g, const Sched& S, const Epi& E) {
;     ...
;             PG8_LDA(At, 1, 1); PG8_STAGE(PG8_SB(1, 0), b3, voffB); PG8_STAGE(PG8_SB(1, 1), b3 + hstep, voffB); PG8_STAGE(PG8_SA(1, 0), a3, voffA);
;             PG8_WAIT_V(8); PG8_WAIT_L(0); PG8_BAR; PG8_MMA(1, 0, At, B0); PG8_MMA(1, 1, At, B1); PG8_BAR; PG8_SCHED;
	s_add_i32 s24, s45, s29
	v_lshl_add_u64 v[170:171], v[170:171], 0, s[14:15]
	s_mov_b32 m0, s24
	ds_read_b128 v[210:213], v193 offset:49152
	ds_read_b128 v[214:217], v193 offset:50176
	ds_read_b128 v[218:221], v193 offset:51200
	ds_read_b128 v[222:225], v193 offset:52224
	ds_read_b128 v[226:229], v193 offset:53248
	ds_read_b128 v[230:233], v193 offset:54272
	ds_read_b128 v[234:237], v193 offset:55296
	ds_read_b128 v[238:241], v193 offset:56320
	global_load_lds_dwordx4 v[170:171], off
	s_add_i32 m0, s24, 0x2000
	s_add_u32 s24, s58, 0x40080
	v_lshl_add_u64 v[170:171], v[242:243], 0, s[14:15]
	s_addc_u32 s25, s59, 0
	s_add_i32 s45, s47, s29
	global_load_lds_dwordx4 v[170:171], off
	v_lshl_add_u64 v[170:171], s[24:25], 0, v[142:143]
	s_mov_b32 m0, s45
	s_nop 0
	global_load_lds_dwordx4 v[170:171], off
	v_lshl_add_u64 v[170:171], s[24:25], 0, v[146:147]
	s_add_i32 m0, s45, 0x2000
	s_nop 0
	global_load_lds_dwordx4 v[170:171], off
	v_lshl_add_u64 v[170:171], v[244:245], 0, s[14:15]
	s_mov_b32 m0, s90
	s_nop 0
	global_load_lds_dwordx4 v[170:171], off
	v_lshl_add_u64 v[170:171], v[246:247], 0, s[14:15]
	s_mov_b32 m0, s91
	s_nop 0
	global_load_lds_dwordx4 v[170:171], off
	s_waitcnt vmcnt(8)
	s_waitcnt lgkmcnt(0)
	s_barrier
	s_setprio 1
	v_mfma_f32_16x16x32_bf16 v[60:63], v[128:131], v[210:213], v[60:63]
	v_mfma_f32_16x16x32_bf16 v[56:59], v[162:165], v[210:213], v[56:59]
	v_mfma_f32_16x16x32_bf16 v[44:47], v[128:131], v[218:221], v[44:47]
	v_mfma_f32_16x16x32_bf16 v[40:43], v[162:165], v[218:221], v[40:43]
	v_mfma_f32_16x16x32_bf16 v[28:31], v[128:131], v[226:229], v[28:31]
	v_mfma_f32_16x16x32_bf16 v[24:27], v[162:165], v[226:229], v[24:27]
	v_mfma_f32_16x16x32_bf16 v[12:15], v[128:131], v[234:237], v[12:15]
	v_mfma_f32_16x16x32_bf16 v[8:11], v[162:165], v[234:237], v[8:11]
	v_mfma_f32_16x16x32_bf16 v[60:63], v[158:161], v[214:217], v[60:63]
	v_mfma_f32_16x16x32_bf16 v[56:59], v[166:169], v[214:217], v[56:59]
	v_mfma_f32_16x16x32_bf16 v[44:47], v[158:161], v[222:225], v[44:47]
	v_mfma_f32_16x16x32_bf16 v[40:43], v[166:169], v[222:225], v[40:43]
	v_mfma_f32_16x16x32_bf16 v[28:31], v[158:161], v[230:233], v[28:31]
	v_mfma_f32_16x16x32_bf16 v[24:27], v[166:169], v[230:233], v[24:27]
	v_mfma_f32_16x16x32_bf16 v[12:15], v[158:161], v[238:241], v[12:15]
	v_mfma_f32_16x16x32_bf16 v[8:11], v[166:169], v[238:241], v[8:11]
	v_mfma_f32_16x16x32_bf16 v[52:55], v[194:197], v[210:213], v[52:55]
	v_mfma_f32_16x16x32_bf16 v[48:51], v[202:205], v[210:213], v[48:51]
	v_mfma_f32_16x16x32_bf16 v[36:39], v[194:197], v[218:221], v[36:39]
	v_mfma_f32_16x16x32_bf16 v[32:35], v[202:205], v[218:221], v[32:35]
	v_mfma_f32_16x16x32_bf16 v[20:23], v[194:197], v[226:229], v[20:23]
	v_mfma_f32_16x16x32_bf16 v[16:19], v[202:205], v[226:229], v[16:19]
	v_mfma_f32_16x16x32_bf16 v[4:7], v[194:197], v[234:237], v[4:7]
	v_mfma_f32_16x16x32_bf16 v[0:3], v[202:205], v[234:237], v[0:3]
	v_mfma_f32_16x16x32_bf16 v[52:55], v[198:201], v[214:217], v[52:55]
	v_mfma_f32_16x16x32_bf16 v[48:51], v[206:209], v[214:217], v[48:51]
	v_mfma_f32_16x16x32_bf16 v[36:39], v[198:201], v[222:225], v[36:39]
	v_mfma_f32_16x16x32_bf16 v[32:35], v[206:209], v[222:225], v[32:35]
	v_mfma_f32_16x16x32_bf16 v[20:23], v[198:201], v[230:233], v[20:23]
	v_mfma_f32_16x16x32_bf16 v[16:19], v[206:209], v[230:233], v[16:19]
	v_mfma_f32_16x16x32_bf16 v[4:7], v[198:201], v[238:241], v[4:7]
	v_mfma_f32_16x16x32_bf16 v[0:3], v[206:209], v[238:241], v[0:3]
	s_setprio 0
	s_barrier
	s_add_i32 s39, s39, 2
	s_add_u32 s56, s56, 0x100
	s_addc_u32 s57, s57, 0
	s_add_u32 s33, s33, 0x100
	s_addc_u32 s37, s37, 0
	s_cmp_gt_u32 s39, 13
